# dense attention loop: drop the vmcnt(3)/(1)/(0) ladder that drained the next tile's K/V prefetch before the LDS writes (full drain only on the last-iteration path)
# baseline (speedup 1.0000x reference)
; #define SBAR() __builtin_amdgcn_sched_barrier(0)
; template <int D0> __device__ __forceinline__ void pv_one(f32x16& od, int vb, bf16x8 pa0, bf16x8 pa1, bf16x8 pa2, bf16x8 pa3) {
;     const s16x4 l0 = tr_read<v_rd_off(D0, 0, 0)>(vb), h0 = tr_read<v_rd_off(D0, 0, 1)>(vb), l1 = tr_read<v_rd_off(D0, 1, 0)>(vb), h1 = tr_read<v_rd_off(D0, 1, 1)>(vb);
;     const s16x4 l2 = tr_read<v_rd_off(D0, 2, 0)>(vb), h2 = tr_read<v_rd_off(D0, 2, 1)>(vb), l3 = tr_read<v_rd_off(D0, 3, 0)>(vb), h3 = tr_read<v_rd_off(D0, 3, 1)>(vb);
;     asm volatile("s_waitcnt lgkmcnt(0)" ::: "memory"); SBAR();
;     ...
;     od = __builtin_amdgcn_mfma_f32_32x32x16_bf16(pa0, PKV(l0, h0), od, 0, 0, 0);
;     od = __builtin_amdgcn_mfma_f32_32x32x16_bf16(pa1, PKV(l1, h1), od, 0, 0, 0);
;     od = __builtin_amdgcn_mfma_f32_32x32x16_bf16(pa2, PKV(l2, h2), od, 0, 0, 0);
;     od = __builtin_amdgcn_mfma_f32_32x32x16_bf16(pa3, PKV(l3, h3), od, 0, 0, 0);
;     ...
; }
.LBB0_536:
	ds_read_b64_tr_b16 v[216:217], v194 offset:0
	ds_read_b64_tr_b16 v[218:219], v194 offset:0x800
	ds_read_b64_tr_b16 v[220:221], v194 offset:0x1000
	ds_read_b64_tr_b16 v[222:223], v194 offset:0x1800
	ds_read_b64_tr_b16 v[224:225], v194 offset:0x2000
	ds_read_b64_tr_b16 v[226:227], v194 offset:0x2800
	ds_read_b64_tr_b16 v[228:229], v194 offset:0x3000
	ds_read_b64_tr_b16 v[230:231], v194 offset:0x3800
	s_waitcnt lgkmcnt(0)
	s_nop 0
	v_mfma_f32_32x32x16_bf16 v[48:63], v[160:163], v[216:219], v[48:63]
	ds_read_b64_tr_b16 v[216:217], v194 offset:0x200
	ds_read_b64_tr_b16 v[218:219], v194 offset:0xa00
	v_mfma_f32_32x32x16_bf16 v[48:63], v[164:167], v[220:223], v[48:63]
	ds_read_b64_tr_b16 v[220:221], v194 offset:0x1200
	ds_read_b64_tr_b16 v[222:223], v194 offset:0x1a00
	v_mfma_f32_32x32x16_bf16 v[48:63], v[168:171], v[224:227], v[48:63]
	ds_read_b64_tr_b16 v[224:225], v194 offset:0x2200
	ds_read_b64_tr_b16 v[226:227], v194 offset:0x2a00
	v_mfma_f32_32x32x16_bf16 v[48:63], v[172:175], v[228:231], v[48:63]
	ds_read_b64_tr_b16 v[228:229], v194 offset:0x3200
	ds_read_b64_tr_b16 v[230:231], v194 offset:0x3a00
	s_waitcnt lgkmcnt(0)
	v_mfma_f32_32x32x16_bf16 v[32:47], v[160:163], v[216:219], v[32:47]
	ds_read_b64_tr_b16 v[216:217], v194 offset:0x400
	ds_read_b64_tr_b16 v[218:219], v194 offset:0xc00
	v_mfma_f32_32x32x16_bf16 v[32:47], v[164:167], v[220:223], v[32:47]
	ds_read_b64_tr_b16 v[220:221], v194 offset:0x1400
	ds_read_b64_tr_b16 v[222:223], v194 offset:0x1c00
	v_mfma_f32_32x32x16_bf16 v[32:47], v[168:171], v[224:227], v[32:47]
	ds_read_b64_tr_b16 v[224:225], v194 offset:0x2400
	ds_read_b64_tr_b16 v[226:227], v194 offset:0x2c00
	v_mfma_f32_32x32x16_bf16 v[32:47], v[172:175], v[228:231], v[32:47]
	ds_read_b64_tr_b16 v[228:229], v194 offset:0x3400
	ds_read_b64_tr_b16 v[230:231], v194 offset:0x3c00
	s_waitcnt lgkmcnt(0)
	v_mfma_f32_32x32x16_bf16 v[16:31], v[160:163], v[216:219], v[16:31]
	ds_read_b64_tr_b16 v[216:217], v194 offset:0x600
	ds_read_b64_tr_b16 v[218:219], v194 offset:0xe00
	v_mfma_f32_32x32x16_bf16 v[16:31], v[164:167], v[220:223], v[16:31]
	ds_read_b64_tr_b16 v[220:221], v194 offset:0x1600
	ds_read_b64_tr_b16 v[222:223], v194 offset:0x1e00
	v_mfma_f32_32x32x16_bf16 v[16:31], v[168:171], v[224:227], v[16:31]
	ds_read_b64_tr_b16 v[224:225], v194 offset:0x2600
	ds_read_b64_tr_b16 v[226:227], v194 offset:0x2e00
	v_mfma_f32_32x32x16_bf16 v[16:31], v[172:175], v[228:231], v[16:31]
	ds_read_b64_tr_b16 v[228:229], v194 offset:0x3600
	ds_read_b64_tr_b16 v[230:231], v194 offset:0x3e00
	s_waitcnt lgkmcnt(0)
	v_mfma_f32_32x32x16_bf16 v[0:15], v[160:163], v[216:219], v[0:15]
	v_max_f32_e32 v160, v81, v81
	v_max_f32_e32 v161, v80, v80
	v_max_f32_e32 v160, v161, v160
	v_max3_f32 v160, v160, v82, v83
	v_max3_f32 v160, v160, v84, v85
	v_max3_f32 v160, v160, v86, v87
	v_max3_f32 v160, v160, v88, v89
	v_max3_f32 v160, v160, v90, v91
	v_max3_f32 v160, v160, v92, v93
	v_mfma_f32_32x32x16_bf16 v[0:15], v[164:167], v[220:223], v[0:15]
	v_max3_f32 v160, v160, v94, v95
	v_max3_f32 v160, v160, v64, v65
	v_max3_f32 v160, v160, v66, v67
	v_max3_f32 v160, v160, v68, v69
	v_max3_f32 v160, v160, v70, v71
	v_max3_f32 v160, v160, v72, v73
	v_max3_f32 v160, v160, v74, v75
	v_max3_f32 v160, v160, v76, v77
	v_mfma_f32_32x32x16_bf16 v[0:15], v[168:171], v[224:227], v[0:15]
	v_max3_f32 v160, v160, v78, v79
	v_mov_b32_e32 v161, v160
	s_nop 1
	v_permlane32_swap_b32_e32 v160, v161
	v_max_f32_e32 v161, v161, v161
	v_max_f32_e32 v160, v160, v160
	v_max_f32_e32 v160, v160, v161
	v_sub_f32_e32 v161, v160, v212
	v_cmp_ge_f32_e32 vcc, s70, v161
	v_max_f32_e32 v161, v212, v212
	v_max_f32_e32 v161, v161, v160
	v_mfma_f32_32x32x16_bf16 v[0:15], v[172:175], v[228:231], v[0:15]
	v_sub_f32_e32 v160, v212, v161
	v_mul_f32_e32 v160, 0x3e0293ee, v160
	v_exp_f32_e32 v160, v160
	s_cmp_eq_u64 vcc, exec
	s_cselect_b64 s[4:5], -1, 0
	s_barrier
	s_waitcnt vmcnt(4)
	v_cndmask_b32_e64 v160, v160, 1.0, s[4:5]
	v_cmp_gt_f32_e32 vcc, 1.0, v160
	ds_write_b128 v198, v[144:147] offset:16384
	ds_write_b128 v199, v[156:159] offset:16384
	ds_write_b128 v196, v[148:151] offset:49152
	ds_write_b128 v197, v[152:155] offset:49152
	s_cbranch_vccz .LBB0_540
	s_and_saveexec_b64 s[14:15], s[0:1]
	ds_write_b32 v185, v160 offset:128
	s_or_b64 exec, exec, s[14:15]
	s_waitcnt lgkmcnt(0)
	v_add_u32_e32 v156, v192, v178
	ds_read_b128 v[144:147], v156 offset:224
	ds_read_b128 v[148:151], v156 offset:192
	ds_read_b128 v[152:155], v156 offset:160
	ds_read_b128 v[156:159], v156 offset:128
	s_waitcnt lgkmcnt(3)
	v_pk_mul_f32 v[60:61], v[60:61], v[144:145]
	s_waitcnt lgkmcnt(2)
	v_pk_mul_f32 v[56:57], v[56:57], v[148:149]
	s_waitcnt lgkmcnt(1)
	v_pk_mul_f32 v[52:53], v[52:53], v[152:153]
	v_pk_mul_f32 v[62:63], v[62:63], v[146:147]
	v_pk_mul_f32 v[58:59], v[58:59], v[150:151]
	v_pk_mul_f32 v[54:55], v[54:55], v[154:155]
	s_waitcnt lgkmcnt(0)
	v_pk_mul_f32 v[50:51], v[50:51], v[158:159]
	v_pk_mul_f32 v[48:49], v[48:49], v[156:157]
	v_pk_mul_f32 v[44:45], v[44:45], v[144:145]
	v_pk_mul_f32 v[40:41], v[40:41], v[148:149]
	v_pk_mul_f32 v[36:37], v[36:37], v[152:153]
	v_pk_mul_f32 v[46:47], v[46:47], v[146:147]
	v_pk_mul_f32 v[42:43], v[42:43], v[150:151]
	v_pk_mul_f32 v[38:39], v[38:39], v[154:155]
	v_pk_mul_f32 v[34:35], v[34:35], v[158:159]
	v_pk_mul_f32 v[32:33], v[32:33], v[156:157]
	v_pk_mul_f32 v[28:29], v[28:29], v[144:145]
	v_pk_mul_f32 v[24:25], v[24:25], v[148:149]
	v_pk_mul_f32 v[20:21], v[20:21], v[152:153]
	v_pk_mul_f32 v[30:31], v[30:31], v[146:147]
	v_pk_mul_f32 v[26:27], v[26:27], v[150:151]
	v_pk_mul_f32 v[22:23], v[22:23], v[154:155]
	v_pk_mul_f32 v[18:19], v[18:19], v[158:159]
	v_pk_mul_f32 v[16:17], v[16:17], v[156:157]
	v_pk_mul_f32 v[12:13], v[12:13], v[144:145]
	v_pk_mul_f32 v[8:9], v[8:9], v[148:149]
	v_pk_mul_f32 v[4:5], v[4:5], v[152:153]
	v_pk_mul_f32 v[14:15], v[14:15], v[146:147]
	v_pk_mul_f32 v[10:11], v[10:11], v[150:151]
	v_pk_mul_f32 v[6:7], v[6:7], v[154:155]
	v_pk_mul_f32 v[2:3], v[2:3], v[158:159]
	v_pk_mul_f32 v[0:1], v[0:1], v[156:157]

; #define SBAR() __builtin_amdgcn_sched_barrier(0)
; #define SLOAD(i, k0) do { sr_[i].vs0 = ld8(&Vh[(long)((k0) + sr) * LDK + sc]); sr_[i].vs1 = ld8(&Vh[(long)((k0) + 32 + sr) * LDK + sc]); \
;     sr_[i].ks0 = ld8(&Kh[(long)((k0) + sr) * LDK + sc]); sr_[i].ks1 = ld8(&Kh[(long)((k0) + 32 + sr) * LDK + sc]); } while (0)
; #define SWRITE(b, i) do { *(bf16x8*)((char*)V_lds + (b) * SHM_V + vst0) = sr_[i].vs0;          \
;     *(bf16x8*)((char*)V_lds + (b) * SHM_V + vst1) = sr_[i].vs1; int kc = sc * 2;               \
;     *(bf16x8*)((char*)K_lds + (b) * SHM_K + KSWZ(sr, kc)) = sr_[i].ks0;                       \
;     *(bf16x8*)((char*)K_lds + (b) * SHM_K + KSWZ(32 + sr, kc)) = sr_[i].ks1; } while (0)
; #define SWAIT() asm volatile("s_waitcnt vmcnt(4)" ::: "memory")
; #define RESC(a) do { if (__any((a) < 1.f)) { if (hi == 0) al_l[r32] = (a); asm volatile("s_waitcnt lgkmcnt(0)" ::: "memory"); \
;     _Pragma("unroll") for (int d = 0; d < 4; ++d) _Pragma("unroll") for (int r = 0; r < 16; ++r) o[d][r] *= al_l[crow(r, hi)]; } } while (0)
; __device__ __forceinline__ void attn_dense_body(const bf16_t* Qb, const bf16_t* Kh, const bf16_t* Vh, bf16_t* Ob, int seq, char* lds) {
;     ...
;     for (int j = 1; j + 1 < NT; j += 2) {
;         SBAR(); qkt(pB0, pB1, (bf16_t*)((char*)K_lds + SHM_K), qr, r32, hi);
;         finishSM(pA0, pA1, alA, l_reg, pa0, pa1, pa2, pa3); SBAR();
;         SLOAD(SO, (j + 2) * KVBLK); SBAR();
;         pv_d0(o, vb0, pa0, pa1, pa2, pa3); partialSM(pB0, pB1, m_reg, mnB, alB);
;         __syncthreads(); SWAIT(); SWRITE(0, SE);
;         RESC(alB); __syncthreads();
;         SBAR(); qkt(pA0, pA1, K_lds, qr, r32, hi);
;         finishSM(pB0, pB1, alB, l_reg, pa0, pa1, pa2, pa3); SBAR();
;         if (j + 3 < NT) SLOAD(SE, (j + 3) * KVBLK); SBAR();
;         pv_d0(o, vb0 + (int)SHM_V, pa0, pa1, pa2, pa3); partialSM(pA0, pA1, m_reg, mnA, alA);
;         __syncthreads(); SWAIT(); SWRITE(1, SO);
;         RESC(alA); __syncthreads();
.Lse_skip:
	s_waitcnt vmcnt(0)
	s_branch .LBB0_536
